# attention: K and V^T LDS fragment reads routed through four spare quads (four reads in flight ahead of each MFMA chain, counted lgkmcnt per MFMA); the -m init block back to per-half-step moves
# baseline (speedup 1.0000x reference)
.LBB0_547:
	ds_read_b128 v[234:237], v137
	ds_read_b128 v[238:241], v137 offset:4608
	ds_read_b128 v[242:245], v137 offset:32
	ds_read_b128 v[246:249], v137 offset:4640
	v_xor_b32_e32 v48, 0x80000000, v0
	v_mov_b32_e32 v49, v48
	v_mov_b32_e32 v50, v48
	v_mov_b32_e32 v51, v48
	v_mov_b32_e32 v52, v48
	v_mov_b32_e32 v53, v48
	v_mov_b32_e32 v54, v48
	v_mov_b32_e32 v55, v48
	v_mov_b32_e32 v56, v48
	v_mov_b32_e32 v57, v48
	v_mov_b32_e32 v58, v48
	v_mov_b32_e32 v59, v48
	v_mov_b32_e32 v60, v48
	v_mov_b32_e32 v61, v48
	v_mov_b32_e32 v62, v48
	v_mov_b32_e32 v63, v48
	s_nop 0
	s_waitcnt lgkmcnt(3)
	v_mfma_f32_32x32x16_bf16 v[64:79], v[234:237], v[80:83], v[48:63]
	ds_read_b128 v[234:237], v137 offset:64
	s_waitcnt lgkmcnt(3)
	v_mfma_f32_32x32x16_bf16 v[48:63], v[238:241], v[80:83], v[48:63]
	ds_read_b128 v[238:241], v137 offset:4672
	s_waitcnt lgkmcnt(3)
	v_mfma_f32_32x32x16_bf16 v[64:79], v[242:245], v[84:87], v[64:79]
	ds_read_b128 v[242:245], v137 offset:4704
	s_waitcnt lgkmcnt(3)
	v_mfma_f32_32x32x16_bf16 v[48:63], v[246:249], v[84:87], v[48:63]
	ds_read_b128 v[246:249], v137 offset:96
	s_waitcnt lgkmcnt(3)
	v_mfma_f32_32x32x16_bf16 v[64:79], v[234:237], v[88:91], v[64:79]
	s_waitcnt lgkmcnt(2)
	v_mfma_f32_32x32x16_bf16 v[48:63], v[238:241], v[88:91], v[48:63]
	s_waitcnt lgkmcnt(1)
	v_mfma_f32_32x32x16_bf16 v[48:63], v[242:245], v[92:95], v[48:63]
	s_waitcnt lgkmcnt(0)
	v_mfma_f32_32x32x16_bf16 v[64:79], v[246:249], v[92:95], v[64:79]
	s_nop 10
	v_max_f32_e32 v2, v48, v48
	v_max_f32_e32 v3, v64, v64
	v_max_f32_e32 v2, v3, v2
	v_max3_f32 v2, v2, v65, v49
	v_max3_f32 v2, v2, v66, v50
	v_max3_f32 v2, v2, v67, v51
	v_max3_f32 v2, v2, v68, v52
	v_max3_f32 v2, v2, v69, v53
	v_max3_f32 v2, v2, v70, v54
	v_max3_f32 v2, v2, v71, v55
	v_max3_f32 v2, v2, v72, v56
	v_max3_f32 v2, v2, v73, v57
	v_max3_f32 v2, v2, v74, v58
	v_max3_f32 v2, v2, v75, v59
	v_max3_f32 v2, v2, v76, v60
	v_max3_f32 v2, v2, v77, v61
	v_max3_f32 v2, v2, v78, v62
	v_max3_f32 v2, v2, v79, v63
	ds_bpermute_b32 v3, v116, v2
	s_waitcnt lgkmcnt(0)
	v_max_f32_e32 v3, v3, v3
	v_max_f32_e32 v2, v2, v3
	v_cmp_lt_f32_e32 vcc, s26, v2
	s_cbranch_vccz .LBB0_549
	v_max_f32_e32 v2, v2, v2
	v_max_f32_e32 v2, 0, v2
	v_exp_f32_e64 v4, -v2
	v_pk_add_f32 v[64:65], v[64:65], v[2:3] op_sel_hi:[1,0] neg_lo:[0,1] neg_hi:[0,1]
	v_pk_add_f32 v[48:49], v[48:49], v[2:3] op_sel_hi:[1,0] neg_lo:[0,1] neg_hi:[0,1]
	v_pk_add_f32 v[66:67], v[66:67], v[2:3] op_sel_hi:[1,0] neg_lo:[0,1] neg_hi:[0,1]
	v_pk_add_f32 v[50:51], v[50:51], v[2:3] op_sel_hi:[1,0] neg_lo:[0,1] neg_hi:[0,1]
	v_pk_add_f32 v[68:69], v[68:69], v[2:3] op_sel_hi:[1,0] neg_lo:[0,1] neg_hi:[0,1]
	v_pk_add_f32 v[52:53], v[52:53], v[2:3] op_sel_hi:[1,0] neg_lo:[0,1] neg_hi:[0,1]
	v_pk_add_f32 v[70:71], v[70:71], v[2:3] op_sel_hi:[1,0] neg_lo:[0,1] neg_hi:[0,1]
	v_pk_add_f32 v[54:55], v[54:55], v[2:3] op_sel_hi:[1,0] neg_lo:[0,1] neg_hi:[0,1]
	v_pk_add_f32 v[72:73], v[72:73], v[2:3] op_sel_hi:[1,0] neg_lo:[0,1] neg_hi:[0,1]
	v_pk_add_f32 v[56:57], v[56:57], v[2:3] op_sel_hi:[1,0] neg_lo:[0,1] neg_hi:[0,1]
	v_pk_add_f32 v[74:75], v[74:75], v[2:3] op_sel_hi:[1,0] neg_lo:[0,1] neg_hi:[0,1]
	v_pk_add_f32 v[58:59], v[58:59], v[2:3] op_sel_hi:[1,0] neg_lo:[0,1] neg_hi:[0,1]
	v_pk_add_f32 v[76:77], v[76:77], v[2:3] op_sel_hi:[1,0] neg_lo:[0,1] neg_hi:[0,1]
	v_pk_add_f32 v[60:61], v[60:61], v[2:3] op_sel_hi:[1,0] neg_lo:[0,1] neg_hi:[0,1]
	v_pk_mul_f32 v[46:47], v[46:47], v[4:5] op_sel_hi:[1,0]
	v_pk_mul_f32 v[44:45], v[44:45], v[4:5] op_sel_hi:[1,0]
	v_pk_mul_f32 v[42:43], v[42:43], v[4:5] op_sel_hi:[1,0]
	v_pk_mul_f32 v[40:41], v[40:41], v[4:5] op_sel_hi:[1,0]
	v_pk_mul_f32 v[38:39], v[38:39], v[4:5] op_sel_hi:[1,0]
	v_pk_mul_f32 v[36:37], v[36:37], v[4:5] op_sel_hi:[1,0]
	v_pk_mul_f32 v[34:35], v[34:35], v[4:5] op_sel_hi:[1,0]
	v_pk_mul_f32 v[32:33], v[32:33], v[4:5] op_sel_hi:[1,0]
	v_pk_mul_f32 v[30:31], v[30:31], v[4:5] op_sel_hi:[1,0]
	v_pk_mul_f32 v[28:29], v[28:29], v[4:5] op_sel_hi:[1,0]
	v_pk_mul_f32 v[26:27], v[26:27], v[4:5] op_sel_hi:[1,0]
	v_pk_mul_f32 v[24:25], v[24:25], v[4:5] op_sel_hi:[1,0]
	v_pk_mul_f32 v[22:23], v[22:23], v[4:5] op_sel_hi:[1,0]
	v_pk_mul_f32 v[20:21], v[20:21], v[4:5] op_sel_hi:[1,0]
	v_pk_mul_f32 v[18:19], v[18:19], v[4:5] op_sel_hi:[1,0]
	v_pk_mul_f32 v[16:17], v[16:17], v[4:5] op_sel_hi:[1,0]
	v_pk_add_f32 v[78:79], v[78:79], v[2:3] op_sel_hi:[1,0] neg_lo:[0,1] neg_hi:[0,1]
	v_pk_add_f32 v[62:63], v[62:63], v[2:3] op_sel_hi:[1,0] neg_lo:[0,1] neg_hi:[0,1]
	v_mul_f32_e32 v117, v117, v4
	v_add_f32_e32 v0, v0, v2
.LBB0_549:
	v_add_u32_e32 v185, 0x2000, v137
	ds_read_b128 v[234:237], v185 offset:1024
	v_add_u32_e32 v186, 0x3000, v137
	ds_read_b128 v[238:241], v186 offset:1536
	ds_read_b128 v[242:245], v185 offset:1056
	ds_read_b128 v[246:249], v186 offset:1568
	v_exp_f32_e32 v6, v64
	v_exp_f32_e32 v7, v65
	v_exp_f32_e32 v8, v66
	v_exp_f32_e32 v9, v67
	v_exp_f32_e32 v2, v68
	v_exp_f32_e32 v3, v69
	v_exp_f32_e32 v4, v70
	v_exp_f32_e32 v5, v71
	v_cvt_pk_bf16_f32 v64, v6, v7
	v_cvt_pk_bf16_f32 v65, v8, v9
	v_cvt_pk_bf16_f32 v66, v2, v3
	v_cvt_pk_bf16_f32 v67, v4, v5
	s_nop 1
	v_exp_f32_e32 v15, v72
	v_exp_f32_e32 v10, v73
	v_exp_f32_e32 v11, v74
	s_waitcnt lgkmcnt(3)
	v_mfma_f32_32x32x16_bf16 v[32:47], v[234:237], v[64:67], v[32:47]
	ds_read_b128 v[234:237], v185 offset:1088
	v_exp_f32_e32 v119, v75
	v_exp_f32_e32 v120, v76
	v_exp_f32_e32 v121, v77
	v_exp_f32_e32 v122, v78
	v_exp_f32_e32 v118, v79
	v_exp_f32_e32 v123, v48
	v_exp_f32_e32 v171, v51
	s_waitcnt lgkmcnt(3)
	v_mfma_f32_32x32x16_bf16 v[16:31], v[238:241], v[64:67], v[16:31]
	ds_read_b128 v[238:241], v186 offset:1600
	v_cvt_pk_bf16_f32 v64, v15, v10
	v_cvt_pk_bf16_f32 v65, v11, v119
	v_cvt_pk_bf16_f32 v66, v120, v121
	v_cvt_pk_bf16_f32 v67, v122, v118
	s_nop 1
	v_exp_f32_e32 v124, v49
	v_exp_f32_e32 v125, v50
	v_exp_f32_e32 v173, v52
	v_exp_f32_e32 v175, v53
	s_waitcnt lgkmcnt(3)
	v_mfma_f32_32x32x16_bf16 v[32:47], v[242:245], v[64:67], v[32:47]
	ds_read_b128 v[242:245], v185 offset:1120
	v_exp_f32_e32 v126, v54
	v_exp_f32_e32 v127, v55
	v_cvt_pk_bf16_f32 v48, v123, v124
	v_cvt_pk_bf16_f32 v49, v125, v171
	v_cvt_pk_bf16_f32 v50, v173, v175
	v_cvt_pk_bf16_f32 v51, v126, v127
	s_nop 1
	v_exp_f32_e32 v177, v56
	v_exp_f32_e32 v179, v57
	v_exp_f32_e32 v182, v58
	s_waitcnt lgkmcnt(3)
	v_mfma_f32_32x32x16_bf16 v[16:31], v[246:249], v[64:67], v[16:31]
	ds_read_b128 v[246:249], v186 offset:1632
	v_exp_f32_e32 v183, v59
	v_exp_f32_e32 v184, v60
	v_exp_f32_e32 v12, v61
	v_exp_f32_e32 v13, v62
	v_exp_f32_e32 v14, v63
	s_add_i32 s16, s28, -1
	s_waitcnt lgkmcnt(3)
	v_mfma_f32_32x32x16_bf16 v[32:47], v[234:237], v[48:51], v[32:47]
	v_cmp_lt_u32_e32 vcc, s16, v204
	s_waitcnt lgkmcnt(2)
	v_mfma_f32_32x32x16_bf16 v[16:31], v[238:241], v[48:51], v[16:31]
	v_cvt_pk_bf16_f32 v48, v177, v179
	v_cvt_pk_bf16_f32 v49, v182, v183
	v_cvt_pk_bf16_f32 v50, v184, v12
	v_cvt_pk_bf16_f32 v51, v13, v14
	s_nop 1
	s_waitcnt lgkmcnt(1)
	v_mfma_f32_32x32x16_bf16 v[32:47], v[242:245], v[48:51], v[32:47]
	s_waitcnt vmcnt(3)
	ds_write_b128 v139, v[96:99] offset:18432
	s_waitcnt vmcnt(2)
	ds_write_b64 v253, v[104:105] offset:27648
	ds_write_b64 v253, v[106:107] offset:27664
	s_waitcnt lgkmcnt(3)
	v_mfma_f32_32x32x16_bf16 v[16:31], v[246:249], v[48:51], v[16:31]
	s_and_saveexec_b64 s[16:17], vcc
	s_cbranch_execz .LBB0_551
	v_lshl_add_u64 v[50:51], v[114:115], 0, v[160:161]
	v_add_co_u32_e32 v50, vcc, 0x4a3d000, v50
	v_lshl_add_u64 v[48:49], v[112:113], 0, v[160:161]
	s_nop 0
	v_addc_co_u32_e32 v51, vcc, 0, v51, vcc
	v_add_co_u32_e32 v48, vcc, 0x4eb1000, v48
	global_load_dwordx4 v[96:99], v[50:51], off
	s_nop 0
	v_addc_co_u32_e32 v49, vcc, 0, v49, vcc
	global_load_dwordx4 v[104:107], v[48:49], off offset:384
.LBB0_551:
	s_or_b64 exec, exec, s[16:17]
	s_waitcnt lgkmcnt(0)
	s_barrier
	ds_read_b128 v[234:237], v137 offset:18432
	ds_read_b128 v[238:241], v137 offset:23040
	ds_read_b128 v[242:245], v137 offset:18464
	ds_read_b128 v[246:249], v137 offset:23072
	v_xor_b32_e32 v48, 0x80000000, v0
	v_mov_b32_e32 v49, v48
	v_mov_b32_e32 v50, v48
	v_mov_b32_e32 v51, v48
	v_mov_b32_e32 v52, v48
	v_mov_b32_e32 v53, v48
	v_mov_b32_e32 v54, v48
	v_mov_b32_e32 v55, v48
	v_mov_b32_e32 v56, v48
	v_mov_b32_e32 v57, v48
	v_mov_b32_e32 v58, v48
	v_mov_b32_e32 v59, v48
	v_mov_b32_e32 v60, v48
	v_mov_b32_e32 v61, v48
	v_mov_b32_e32 v62, v48
	v_mov_b32_e32 v63, v48
	v_add_f32_e32 v6, 0, v6
	v_add_f32_e32 v6, v6, v7
	s_waitcnt lgkmcnt(3)
	v_mfma_f32_32x32x16_bf16 v[64:79], v[234:237], v[80:83], v[48:63]
	ds_read_b128 v[234:237], v137 offset:18496
	v_add_f32_e32 v6, v8, v6
	v_add_f32_e32 v185, v9, v6
	v_add_f32_e32 v2, v2, v185
	v_add_f32_e32 v2, v3, v2
	v_add_f32_e32 v2, v4, v2
	s_waitcnt lgkmcnt(3)
	v_mfma_f32_32x32x16_bf16 v[48:63], v[238:241], v[80:83], v[48:63]
	ds_read_b128 v[238:241], v137 offset:23104
	v_add_f32_e32 v2, v5, v2
	v_add_f32_e32 v15, v15, v2
	s_waitcnt lgkmcnt(3)
	v_mfma_f32_32x32x16_bf16 v[64:79], v[242:245], v[84:87], v[64:79]
	ds_read_b128 v[242:245], v137 offset:18528
	s_waitcnt lgkmcnt(3)
	v_mfma_f32_32x32x16_bf16 v[48:63], v[246:249], v[84:87], v[48:63]
	ds_read_b128 v[246:249], v137 offset:23136
	s_waitcnt lgkmcnt(3)
	v_mfma_f32_32x32x16_bf16 v[64:79], v[234:237], v[88:91], v[64:79]
	v_add_f32_e32 v6, v10, v15
	v_add_f32_e32 v6, v11, v6
	v_add_f32_e32 v6, v119, v6
	v_add_f32_e32 v6, v120, v6
	v_add_f32_e32 v6, v121, v6
	v_add_f32_e32 v10, v122, v6
	s_waitcnt lgkmcnt(2)
	v_mfma_f32_32x32x16_bf16 v[48:63], v[238:241], v[88:91], v[48:63]
	v_add_f32_e32 v2, v118, v10
	v_add_f32_e32 v2, v123, v2
	v_add_f32_e32 v2, v124, v2
	v_add_f32_e32 v2, v125, v2
	v_add_f32_e32 v2, v171, v2
	v_add_f32_e32 v2, v173, v2
	v_add_f32_e32 v2, v175, v2
	s_waitcnt lgkmcnt(1)
	v_mfma_f32_32x32x16_bf16 v[64:79], v[242:245], v[92:95], v[64:79]
	v_add_f32_e32 v2, v126, v2
	v_add_f32_e32 v2, v127, v2
	v_add_f32_e32 v2, v177, v2
	v_add_f32_e32 v2, v179, v2
	v_add_f32_e32 v2, v182, v2
	v_add_f32_e32 v2, v183, v2
	v_add_f32_e32 v2, v184, v2
	s_waitcnt lgkmcnt(0)
	v_mfma_f32_32x32x16_bf16 v[48:63], v[246:249], v[92:95], v[48:63]
	s_nop 2
	v_max_f32_e32 v4, v64, v64
	v_add_f32_e32 v2, v12, v2
	v_add_f32_e32 v2, v13, v2
	v_add_f32_e32 v2, v14, v2
	v_add_f32_e32 v2, v117, v2
	s_nop 3
	v_max_f32_e32 v3, v48, v48
	v_max_f32_e32 v3, v4, v3
	v_max3_f32 v3, v3, v65, v49
	v_max3_f32 v3, v3, v66, v50
	v_max3_f32 v3, v3, v67, v51
	v_max3_f32 v3, v3, v68, v52
	v_max3_f32 v3, v3, v69, v53
	v_max3_f32 v3, v3, v70, v54
	v_max3_f32 v3, v3, v71, v55
	v_max3_f32 v3, v3, v72, v56
	v_max3_f32 v3, v3, v73, v57
	v_max3_f32 v3, v3, v74, v58
	v_max3_f32 v3, v3, v75, v59
	v_max3_f32 v3, v3, v76, v60
	v_max3_f32 v3, v3, v77, v61
	v_max3_f32 v3, v3, v78, v62
	v_max3_f32 v3, v3, v79, v63
	ds_bpermute_b32 v4, v116, v3
	s_waitcnt lgkmcnt(0)
	v_max_f32_e32 v4, v4, v4
	v_max_f32_e32 v3, v3, v4
	v_cmp_lt_f32_e32 vcc, s26, v3
	s_cbranch_vccz .LBB0_553
	v_max_f32_e32 v3, v3, v3
	v_max_f32_e32 v4, 0, v3
	v_exp_f32_e64 v6, -v4
	v_pk_add_f32 v[64:65], v[64:65], v[4:5] op_sel_hi:[1,0] neg_lo:[0,1] neg_hi:[0,1]
	v_pk_add_f32 v[48:49], v[48:49], v[4:5] op_sel_hi:[1,0] neg_lo:[0,1] neg_hi:[0,1]
	v_pk_add_f32 v[66:67], v[66:67], v[4:5] op_sel_hi:[1,0] neg_lo:[0,1] neg_hi:[0,1]
	v_pk_add_f32 v[50:51], v[50:51], v[4:5] op_sel_hi:[1,0] neg_lo:[0,1] neg_hi:[0,1]
	v_pk_add_f32 v[68:69], v[68:69], v[4:5] op_sel_hi:[1,0] neg_lo:[0,1] neg_hi:[0,1]
	v_pk_add_f32 v[52:53], v[52:53], v[4:5] op_sel_hi:[1,0] neg_lo:[0,1] neg_hi:[0,1]
	v_pk_add_f32 v[70:71], v[70:71], v[4:5] op_sel_hi:[1,0] neg_lo:[0,1] neg_hi:[0,1]
	v_pk_add_f32 v[54:55], v[54:55], v[4:5] op_sel_hi:[1,0] neg_lo:[0,1] neg_hi:[0,1]
	v_pk_add_f32 v[72:73], v[72:73], v[4:5] op_sel_hi:[1,0] neg_lo:[0,1] neg_hi:[0,1]
	v_pk_add_f32 v[56:57], v[56:57], v[4:5] op_sel_hi:[1,0] neg_lo:[0,1] neg_hi:[0,1]
	v_pk_add_f32 v[74:75], v[74:75], v[4:5] op_sel_hi:[1,0] neg_lo:[0,1] neg_hi:[0,1]
	v_pk_add_f32 v[58:59], v[58:59], v[4:5] op_sel_hi:[1,0] neg_lo:[0,1] neg_hi:[0,1]
	v_pk_add_f32 v[76:77], v[76:77], v[4:5] op_sel_hi:[1,0] neg_lo:[0,1] neg_hi:[0,1]
	v_pk_add_f32 v[60:61], v[60:61], v[4:5] op_sel_hi:[1,0] neg_lo:[0,1] neg_hi:[0,1]
	v_pk_mul_f32 v[46:47], v[46:47], v[6:7] op_sel_hi:[1,0]
	v_pk_mul_f32 v[44:45], v[44:45], v[6:7] op_sel_hi:[1,0]
	v_pk_mul_f32 v[42:43], v[42:43], v[6:7] op_sel_hi:[1,0]
	v_pk_mul_f32 v[40:41], v[40:41], v[6:7] op_sel_hi:[1,0]
	v_pk_mul_f32 v[38:39], v[38:39], v[6:7] op_sel_hi:[1,0]
	v_pk_mul_f32 v[36:37], v[36:37], v[6:7] op_sel_hi:[1,0]
	v_pk_mul_f32 v[34:35], v[34:35], v[6:7] op_sel_hi:[1,0]
	v_pk_mul_f32 v[32:33], v[32:33], v[6:7] op_sel_hi:[1,0]
	v_pk_mul_f32 v[30:31], v[30:31], v[6:7] op_sel_hi:[1,0]
	v_pk_mul_f32 v[28:29], v[28:29], v[6:7] op_sel_hi:[1,0]
	v_pk_mul_f32 v[26:27], v[26:27], v[6:7] op_sel_hi:[1,0]
	v_pk_mul_f32 v[24:25], v[24:25], v[6:7] op_sel_hi:[1,0]
	v_pk_mul_f32 v[22:23], v[22:23], v[6:7] op_sel_hi:[1,0]
	v_pk_mul_f32 v[20:21], v[20:21], v[6:7] op_sel_hi:[1,0]
	v_pk_mul_f32 v[18:19], v[18:19], v[6:7] op_sel_hi:[1,0]
	v_pk_mul_f32 v[16:17], v[16:17], v[6:7] op_sel_hi:[1,0]
	v_pk_add_f32 v[78:79], v[78:79], v[4:5] op_sel_hi:[1,0] neg_lo:[0,1] neg_hi:[0,1]
	v_pk_add_f32 v[62:63], v[62:63], v[4:5] op_sel_hi:[1,0] neg_lo:[0,1] neg_hi:[0,1]
	v_mul_f32_e32 v2, v2, v6
	v_add_f32_e32 v0, v0, v4
.LBB0_553:
	v_add_u32_e32 v117, 0x6800, v137
	ds_read_b128 v[234:237], v117 offset:1024
	v_add_u32_e32 v122, 0x7800, v137
	ds_read_b128 v[238:241], v122 offset:1536
	ds_read_b128 v[242:245], v117 offset:1056
	ds_read_b128 v[246:249], v122 offset:1568
	v_exp_f32_e32 v3, v64
	v_exp_f32_e32 v4, v65
	v_exp_f32_e32 v5, v66
	v_exp_f32_e32 v6, v67
	v_exp_f32_e32 v7, v68
	v_exp_f32_e32 v8, v69
	v_exp_f32_e32 v9, v70
	v_exp_f32_e32 v10, v71
	v_cvt_pk_bf16_f32 v68, v3, v4
	v_cvt_pk_bf16_f32 v69, v5, v6
	v_cvt_pk_bf16_f32 v70, v7, v8
	v_cvt_pk_bf16_f32 v71, v9, v10
	s_nop 1
	v_exp_f32_e32 v11, v72
	v_exp_f32_e32 v12, v73
	v_exp_f32_e32 v13, v74
	s_waitcnt lgkmcnt(3)
	v_mfma_f32_32x32x16_bf16 v[32:47], v[234:237], v[68:71], v[32:47]
	ds_read_b128 v[234:237], v117 offset:1088
	v_exp_f32_e32 v14, v75
	v_exp_f32_e32 v15, v76
	v_exp_f32_e32 v64, v77
	v_exp_f32_e32 v65, v78
	v_exp_f32_e32 v66, v79
	v_exp_f32_e32 v48, v48
	v_exp_f32_e32 v49, v49
	s_waitcnt lgkmcnt(3)
	v_mfma_f32_32x32x16_bf16 v[16:31], v[238:241], v[68:71], v[16:31]
	ds_read_b128 v[238:241], v122 offset:1600
	v_cvt_pk_bf16_f32 v68, v11, v12
	v_cvt_pk_bf16_f32 v69, v13, v14
	v_cvt_pk_bf16_f32 v70, v15, v64
	v_cvt_pk_bf16_f32 v71, v65, v66
	s_nop 1
	v_exp_f32_e32 v50, v50
	v_exp_f32_e32 v51, v51
	v_exp_f32_e32 v52, v52
	v_exp_f32_e32 v53, v53
	s_waitcnt lgkmcnt(3)
	v_mfma_f32_32x32x16_bf16 v[32:47], v[242:245], v[68:71], v[32:47]
	ds_read_b128 v[242:245], v117 offset:1120
	v_exp_f32_e32 v54, v54
	v_exp_f32_e32 v55, v55
	v_exp_f32_e32 v56, v56
	v_exp_f32_e32 v57, v57
	v_exp_f32_e32 v58, v58
	v_exp_f32_e32 v59, v59
	v_exp_f32_e32 v60, v60
	s_waitcnt lgkmcnt(3)
	v_mfma_f32_32x32x16_bf16 v[16:31], v[246:249], v[68:71], v[16:31]
	ds_read_b128 v[246:249], v122 offset:1632
	v_cvt_pk_bf16_f32 v68, v48, v49
	v_cvt_pk_bf16_f32 v69, v50, v51
	v_cvt_pk_bf16_f32 v70, v52, v53
	v_cvt_pk_bf16_f32 v71, v54, v55
	s_nop 1
	v_exp_f32_e32 v61, v61
	v_exp_f32_e32 v62, v62
	v_exp_f32_e32 v63, v63
	s_add_i32 s29, s28, -2
	s_waitcnt lgkmcnt(3)
	v_mfma_f32_32x32x16_bf16 v[32:47], v[234:237], v[68:71], v[32:47]
	v_cmp_lt_u32_e32 vcc, s29, v204
	s_waitcnt lgkmcnt(2)
	v_mfma_f32_32x32x16_bf16 v[16:31], v[238:241], v[68:71], v[16:31]
	v_cvt_pk_bf16_f32 v68, v56, v57
	v_cvt_pk_bf16_f32 v69, v58, v59
	v_cvt_pk_bf16_f32 v70, v60, v61
	v_cvt_pk_bf16_f32 v71, v62, v63
	s_nop 1
	s_waitcnt lgkmcnt(1)
	v_mfma_f32_32x32x16_bf16 v[32:47], v[242:245], v[68:71], v[32:47]
	s_waitcnt lgkmcnt(0)
	v_mfma_f32_32x32x16_bf16 v[16:31], v[246:249], v[68:71], v[16:31]
	s_and_saveexec_b64 s[16:17], vcc
	s_cbranch_execz .LBB0_555
	s_waitcnt vmcnt(2)
	ds_write_b128 v139, v[100:103]
	ds_write_b64 v253, v[108:109] offset:9216
	ds_write_b64 v253, v[110:111] offset:9232

.LBB0_570:
	v_add_u32_e32 v14, v136, v151
	ds_read_b128 v[234:237], v14
	ds_read_b128 v[238:241], v14 offset:6656
	ds_read_b128 v[242:245], v14 offset:32
	ds_read_b128 v[246:249], v14 offset:6688
	v_xor_b32_e32 v48, 0x80000000, v0
	v_mov_b32_e32 v49, v48
	v_mov_b32_e32 v50, v48
	v_mov_b32_e32 v51, v48
	v_mov_b32_e32 v52, v48
	v_mov_b32_e32 v53, v48
	v_mov_b32_e32 v54, v48
	v_mov_b32_e32 v55, v48
	v_mov_b32_e32 v56, v48
	v_mov_b32_e32 v57, v48
	v_mov_b32_e32 v58, v48
	v_mov_b32_e32 v59, v48
	v_mov_b32_e32 v60, v48
	v_mov_b32_e32 v61, v48
	v_mov_b32_e32 v62, v48
	v_mov_b32_e32 v63, v48
	s_nop 0
	s_waitcnt lgkmcnt(3)
	v_mfma_f32_32x32x16_bf16 v[64:79], v[234:237], v[100:103], v[48:63]
	ds_read_b128 v[234:237], v14 offset:64
	s_waitcnt lgkmcnt(3)
	v_mfma_f32_32x32x16_bf16 v[48:63], v[238:241], v[100:103], v[48:63]
	ds_read_b128 v[238:241], v14 offset:6720
	s_waitcnt lgkmcnt(3)
	v_mfma_f32_32x32x16_bf16 v[64:79], v[242:245], v[80:83], v[64:79]
	ds_read_b128 v[242:245], v14 offset:96
	s_waitcnt lgkmcnt(3)
	v_mfma_f32_32x32x16_bf16 v[48:63], v[246:249], v[80:83], v[48:63]
	ds_read_b128 v[246:249], v14 offset:6752
	s_waitcnt lgkmcnt(3)
	v_mfma_f32_32x32x16_bf16 v[64:79], v[234:237], v[84:87], v[64:79]
	ds_read_b128 v[234:237], v14 offset:128
	s_waitcnt lgkmcnt(3)
	v_mfma_f32_32x32x16_bf16 v[48:63], v[238:241], v[84:87], v[48:63]
	ds_read_b128 v[238:241], v14 offset:6784
	s_waitcnt lgkmcnt(3)
	v_mfma_f32_32x32x16_bf16 v[64:79], v[242:245], v[88:91], v[64:79]
	ds_read_b128 v[242:245], v14 offset:6816
	s_waitcnt lgkmcnt(3)
	v_mfma_f32_32x32x16_bf16 v[48:63], v[246:249], v[88:91], v[48:63]
	ds_read_b128 v[246:249], v14 offset:160
	s_waitcnt lgkmcnt(3)
	v_mfma_f32_32x32x16_bf16 v[64:79], v[234:237], v[92:95], v[64:79]
	s_waitcnt lgkmcnt(2)
	v_mfma_f32_32x32x16_bf16 v[48:63], v[238:241], v[92:95], v[48:63]
	s_waitcnt lgkmcnt(1)
	v_mfma_f32_32x32x16_bf16 v[48:63], v[242:245], v[96:99], v[48:63]
	s_waitcnt lgkmcnt(0)
	v_mfma_f32_32x32x16_bf16 v[64:79], v[246:249], v[96:99], v[64:79]
	s_nop 10
	v_max_f32_e32 v2, v48, v48
	v_max_f32_e32 v3, v64, v64
	v_max_f32_e32 v2, v3, v2
	v_max3_f32 v2, v2, v65, v49
	v_max3_f32 v2, v2, v66, v50
	v_max3_f32 v2, v2, v67, v51
	v_max3_f32 v2, v2, v68, v52
	v_max3_f32 v2, v2, v69, v53
	v_max3_f32 v2, v2, v70, v54
	v_max3_f32 v2, v2, v71, v55
	v_max3_f32 v2, v2, v72, v56
	v_max3_f32 v2, v2, v73, v57
	v_max3_f32 v2, v2, v74, v58
	v_max3_f32 v2, v2, v75, v59
	v_max3_f32 v2, v2, v76, v60
	v_max3_f32 v2, v2, v77, v61
	v_max3_f32 v2, v2, v78, v62
	v_max3_f32 v2, v2, v79, v63
	ds_bpermute_b32 v3, v171, v2
	s_waitcnt lgkmcnt(0)
	v_max_f32_e32 v3, v3, v3
	v_max_f32_e32 v2, v2, v3
	v_cmp_lt_f32_e32 vcc, s26, v2
	s_cbranch_vccz .LBB0_572
	v_max_f32_e32 v2, v2, v2
	v_max_f32_e32 v2, 0, v2
	v_exp_f32_e64 v4, -v2
	v_pk_add_f32 v[64:65], v[64:65], v[2:3] op_sel_hi:[1,0] neg_lo:[0,1] neg_hi:[0,1]
	v_pk_add_f32 v[48:49], v[48:49], v[2:3] op_sel_hi:[1,0] neg_lo:[0,1] neg_hi:[0,1]
	v_pk_add_f32 v[66:67], v[66:67], v[2:3] op_sel_hi:[1,0] neg_lo:[0,1] neg_hi:[0,1]
	v_pk_add_f32 v[50:51], v[50:51], v[2:3] op_sel_hi:[1,0] neg_lo:[0,1] neg_hi:[0,1]
	v_pk_add_f32 v[68:69], v[68:69], v[2:3] op_sel_hi:[1,0] neg_lo:[0,1] neg_hi:[0,1]
	v_pk_add_f32 v[52:53], v[52:53], v[2:3] op_sel_hi:[1,0] neg_lo:[0,1] neg_hi:[0,1]
	v_pk_add_f32 v[70:71], v[70:71], v[2:3] op_sel_hi:[1,0] neg_lo:[0,1] neg_hi:[0,1]
	v_pk_add_f32 v[54:55], v[54:55], v[2:3] op_sel_hi:[1,0] neg_lo:[0,1] neg_hi:[0,1]
	v_pk_add_f32 v[72:73], v[72:73], v[2:3] op_sel_hi:[1,0] neg_lo:[0,1] neg_hi:[0,1]
	v_pk_add_f32 v[56:57], v[56:57], v[2:3] op_sel_hi:[1,0] neg_lo:[0,1] neg_hi:[0,1]
	v_pk_add_f32 v[74:75], v[74:75], v[2:3] op_sel_hi:[1,0] neg_lo:[0,1] neg_hi:[0,1]
	v_pk_add_f32 v[58:59], v[58:59], v[2:3] op_sel_hi:[1,0] neg_lo:[0,1] neg_hi:[0,1]
	v_pk_add_f32 v[76:77], v[76:77], v[2:3] op_sel_hi:[1,0] neg_lo:[0,1] neg_hi:[0,1]
	v_pk_add_f32 v[60:61], v[60:61], v[2:3] op_sel_hi:[1,0] neg_lo:[0,1] neg_hi:[0,1]
	v_pk_mul_f32 v[46:47], v[46:47], v[4:5] op_sel_hi:[1,0]
	v_pk_mul_f32 v[44:45], v[44:45], v[4:5] op_sel_hi:[1,0]
	v_pk_mul_f32 v[42:43], v[42:43], v[4:5] op_sel_hi:[1,0]
	v_pk_mul_f32 v[40:41], v[40:41], v[4:5] op_sel_hi:[1,0]
	v_pk_mul_f32 v[38:39], v[38:39], v[4:5] op_sel_hi:[1,0]
	v_pk_mul_f32 v[36:37], v[36:37], v[4:5] op_sel_hi:[1,0]
	v_pk_mul_f32 v[34:35], v[34:35], v[4:5] op_sel_hi:[1,0]
	v_pk_mul_f32 v[32:33], v[32:33], v[4:5] op_sel_hi:[1,0]
	v_pk_mul_f32 v[30:31], v[30:31], v[4:5] op_sel_hi:[1,0]
	v_pk_mul_f32 v[28:29], v[28:29], v[4:5] op_sel_hi:[1,0]
	v_pk_mul_f32 v[26:27], v[26:27], v[4:5] op_sel_hi:[1,0]
	v_pk_mul_f32 v[24:25], v[24:25], v[4:5] op_sel_hi:[1,0]
	v_pk_mul_f32 v[22:23], v[22:23], v[4:5] op_sel_hi:[1,0]
	v_pk_mul_f32 v[20:21], v[20:21], v[4:5] op_sel_hi:[1,0]
	v_pk_mul_f32 v[18:19], v[18:19], v[4:5] op_sel_hi:[1,0]
	v_pk_mul_f32 v[16:17], v[16:17], v[4:5] op_sel_hi:[1,0]
	v_pk_add_f32 v[78:79], v[78:79], v[2:3] op_sel_hi:[1,0] neg_lo:[0,1] neg_hi:[0,1]
	v_pk_add_f32 v[62:63], v[62:63], v[2:3] op_sel_hi:[1,0] neg_lo:[0,1] neg_hi:[0,1]
	v_mul_f32_e32 v173, v173, v4
	v_add_f32_e32 v0, v0, v2
.LBB0_572:
	v_add_u32_e32 v2, v136, v141
	v_add_u32_e32 v221, 0x3000, v2
	ds_read_b128 v[234:237], v221 offset:1024
	v_add_u32_e32 v222, 0x3000, v203
	v_add_u32_e32 v222, v222, v134
	ds_read_b128 v[238:241], v222 offset:1024
	ds_read_b128 v[242:245], v221 offset:1056
	ds_read_b128 v[246:249], v222 offset:1056
	v_exp_f32_e32 v6, v64
	v_exp_f32_e32 v7, v65
	v_exp_f32_e32 v8, v66
	v_exp_f32_e32 v9, v67
	v_exp_f32_e32 v10, v68
	v_exp_f32_e32 v3, v69
	v_exp_f32_e32 v4, v70
	v_exp_f32_e32 v5, v71
	v_cvt_pk_bf16_f32 v64, v6, v7
	v_cvt_pk_bf16_f32 v65, v8, v9
	v_cvt_pk_bf16_f32 v66, v10, v3
	v_cvt_pk_bf16_f32 v67, v4, v5
	s_nop 1
	v_exp_f32_e32 v15, v72
	v_exp_f32_e32 v175, v73
	v_exp_f32_e32 v11, v74
	s_waitcnt lgkmcnt(3)
	v_mfma_f32_32x32x16_bf16 v[32:47], v[234:237], v[64:67], v[32:47]
	ds_read_b128 v[234:237], v221 offset:1088
	v_exp_f32_e32 v177, v75
	v_exp_f32_e32 v179, v76
	v_exp_f32_e32 v205, v77
	v_exp_f32_e32 v206, v78
	v_exp_f32_e32 v207, v79
	v_exp_f32_e32 v212, v51
	v_exp_f32_e32 v213, v52
	s_waitcnt lgkmcnt(3)
	v_mfma_f32_32x32x16_bf16 v[16:31], v[238:241], v[64:67], v[16:31]
	ds_read_b128 v[238:241], v222 offset:1088
	v_cvt_pk_bf16_f32 v64, v15, v175
	v_cvt_pk_bf16_f32 v65, v11, v177
	v_cvt_pk_bf16_f32 v66, v179, v205
	v_cvt_pk_bf16_f32 v67, v206, v207
	s_nop 1
	v_exp_f32_e32 v208, v48
	v_exp_f32_e32 v209, v49
	v_exp_f32_e32 v210, v50
	v_exp_f32_e32 v214, v53
	s_waitcnt lgkmcnt(3)
	v_mfma_f32_32x32x16_bf16 v[32:47], v[242:245], v[64:67], v[32:47]
	ds_read_b128 v[242:245], v221 offset:1120
	v_exp_f32_e32 v215, v54
	v_exp_f32_e32 v211, v55
	v_cvt_pk_bf16_f32 v48, v208, v209
	v_cvt_pk_bf16_f32 v49, v210, v212
	v_cvt_pk_bf16_f32 v50, v213, v214
	v_cvt_pk_bf16_f32 v51, v215, v211
	s_nop 1
	v_exp_f32_e32 v216, v56
	v_exp_f32_e32 v217, v57
	v_exp_f32_e32 v218, v58
	s_waitcnt lgkmcnt(3)
	v_mfma_f32_32x32x16_bf16 v[16:31], v[246:249], v[64:67], v[16:31]
	ds_read_b128 v[246:249], v222 offset:1120
	v_exp_f32_e32 v219, v59
	v_exp_f32_e32 v220, v60
	v_exp_f32_e32 v12, v61
	v_exp_f32_e32 v13, v62
	v_exp_f32_e32 v14, v63
	s_waitcnt lgkmcnt(3)
	v_mfma_f32_32x32x16_bf16 v[32:47], v[234:237], v[48:51], v[32:47]
	s_waitcnt lgkmcnt(2)
	v_mfma_f32_32x32x16_bf16 v[16:31], v[238:241], v[48:51], v[16:31]
	v_cvt_pk_bf16_f32 v48, v216, v217
	v_cvt_pk_bf16_f32 v49, v218, v219
	v_cvt_pk_bf16_f32 v50, v220, v12
	v_cvt_pk_bf16_f32 v51, v13, v14
	s_nop 1
	s_waitcnt lgkmcnt(1)
	v_mfma_f32_32x32x16_bf16 v[32:47], v[242:245], v[48:51], v[32:47]
	s_waitcnt vmcnt(3)
	ds_write_b128 v149, v[108:111] offset:22528
	s_waitcnt lgkmcnt(1)
	v_mfma_f32_32x32x16_bf16 v[16:31], v[246:249], v[48:51], v[16:31]
	s_and_saveexec_b64 s[6:7], s[4:5]
	ds_write_b128 v202, v[104:107] offset:22528
	s_or_b64 exec, exec, s[6:7]
	s_add_i32 s6, s28, 3
	v_cmp_lt_u32_e32 vcc, s6, v204
	s_waitcnt vmcnt(2)
	ds_write_b64 v253, v[120:121] offset:35840
	ds_write_b64 v253, v[122:123] offset:35856
	s_and_saveexec_b64 s[6:7], vcc
	s_cbranch_execz .LBB0_578
	v_lshl_add_u64 v[48:49], s[86:87], 0, v[186:187]
	v_add_co_u32_e32 v48, vcc, 0x8739000, v48
	s_nop 1
	v_addc_co_u32_e32 v49, vcc, 0, v49, vcc
	global_load_dwordx4 v[108:111], v[48:49], off
	s_and_saveexec_b64 s[16:17], s[4:5]
	s_cbranch_execz .LBB0_577
	v_lshl_add_u64 v[48:49], s[86:87], 0, v[182:183]
	v_add_co_u32_e32 v48, vcc, 0x8739000, v48
	s_nop 1
	v_addc_co_u32_e32 v49, vcc, 0, v49, vcc
	global_load_dwordx4 v[104:107], v[48:49], off

.LBB0_578:
	s_or_b64 exec, exec, s[6:7]
	s_waitcnt lgkmcnt(0)
	s_barrier
	ds_read_b128 v[234:237], v198 offset:22528
	ds_read_b128 v[238:241], v198 offset:29184
	ds_read_b128 v[242:245], v198 offset:22560
	ds_read_b128 v[246:249], v198 offset:29216
	v_xor_b32_e32 v48, 0x80000000, v0
	v_mov_b32_e32 v49, v48
	v_mov_b32_e32 v50, v48
	v_mov_b32_e32 v51, v48
	v_mov_b32_e32 v52, v48
	v_mov_b32_e32 v53, v48
	v_mov_b32_e32 v54, v48
	v_mov_b32_e32 v55, v48
	v_mov_b32_e32 v56, v48
	v_mov_b32_e32 v57, v48
	v_mov_b32_e32 v58, v48
	v_mov_b32_e32 v59, v48
	v_mov_b32_e32 v60, v48
	v_mov_b32_e32 v61, v48
	v_mov_b32_e32 v62, v48
	v_mov_b32_e32 v63, v48
	v_add_f32_e32 v6, 0, v6
	v_add_f32_e32 v6, v6, v7
	s_waitcnt lgkmcnt(3)
	v_mfma_f32_32x32x16_bf16 v[64:79], v[234:237], v[100:103], v[48:63]
	ds_read_b128 v[234:237], v198 offset:22592
	v_add_f32_e32 v6, v8, v6
	v_add_f32_e32 v6, v9, v6
	v_add_f32_e32 v10, v10, v6
	v_add_f32_e32 v3, v3, v10
	v_add_f32_e32 v3, v4, v3
	v_add_f32_e32 v3, v5, v3
	s_waitcnt lgkmcnt(3)
	v_mfma_f32_32x32x16_bf16 v[48:63], v[238:241], v[100:103], v[48:63]
	ds_read_b128 v[238:241], v198 offset:29248
	v_add_f32_e32 v3, v15, v3
	v_add_f32_e32 v3, v175, v3
	v_add_f32_e32 v3, v11, v3
	v_add_f32_e32 v3, v177, v3
	v_add_f32_e32 v3, v179, v3
	v_add_f32_e32 v3, v205, v3
	v_add_f32_e32 v3, v206, v3
	s_waitcnt lgkmcnt(3)
	v_mfma_f32_32x32x16_bf16 v[64:79], v[242:245], v[80:83], v[64:79]
	ds_read_b128 v[242:245], v198 offset:22624
	v_add_f32_e32 v3, v207, v3
	v_add_f32_e32 v3, v208, v3
	v_add_f32_e32 v3, v209, v3
	v_add_f32_e32 v3, v210, v3
	v_add_f32_e32 v3, v212, v3
	v_add_f32_e32 v3, v213, v3
	s_waitcnt lgkmcnt(3)
	v_mfma_f32_32x32x16_bf16 v[48:63], v[246:249], v[80:83], v[48:63]
	ds_read_b128 v[246:249], v198 offset:29280
	v_add_f32_e32 v3, v214, v3
	v_add_f32_e32 v3, v215, v3
	v_add_f32_e32 v3, v211, v3
	v_add_f32_e32 v3, v216, v3
	v_add_f32_e32 v3, v217, v3
	v_add_f32_e32 v3, v218, v3
	v_add_f32_e32 v3, v219, v3
	s_waitcnt lgkmcnt(3)
	v_mfma_f32_32x32x16_bf16 v[64:79], v[234:237], v[84:87], v[64:79]
	ds_read_b128 v[234:237], v198 offset:22656
	v_add_f32_e32 v3, v220, v3
	v_add_f32_e32 v3, v12, v3
	v_add_f32_e32 v3, v13, v3
	v_add_f32_e32 v3, v14, v3
	v_add_f32_e32 v3, v173, v3
	s_waitcnt lgkmcnt(3)
	v_mfma_f32_32x32x16_bf16 v[48:63], v[238:241], v[84:87], v[48:63]
	ds_read_b128 v[238:241], v198 offset:29312
	s_waitcnt lgkmcnt(3)
	v_mfma_f32_32x32x16_bf16 v[64:79], v[242:245], v[88:91], v[64:79]
	ds_read_b128 v[242:245], v198 offset:29344
	s_waitcnt lgkmcnt(3)
	v_mfma_f32_32x32x16_bf16 v[48:63], v[246:249], v[88:91], v[48:63]
	ds_read_b128 v[246:249], v198 offset:22688
	s_waitcnt lgkmcnt(3)
	v_mfma_f32_32x32x16_bf16 v[64:79], v[234:237], v[92:95], v[64:79]
	s_waitcnt lgkmcnt(2)
	v_mfma_f32_32x32x16_bf16 v[48:63], v[238:241], v[92:95], v[48:63]
	s_waitcnt lgkmcnt(1)
	v_mfma_f32_32x32x16_bf16 v[48:63], v[242:245], v[96:99], v[48:63]
	s_waitcnt lgkmcnt(0)
	v_mfma_f32_32x32x16_bf16 v[64:79], v[246:249], v[96:99], v[64:79]
	s_nop 10
	v_max_f32_e32 v4, v48, v48
	v_max_f32_e32 v5, v64, v64
	v_max_f32_e32 v4, v5, v4
	v_max3_f32 v4, v4, v65, v49
	v_max3_f32 v4, v4, v66, v50
	v_max3_f32 v4, v4, v67, v51
	v_max3_f32 v4, v4, v68, v52
	v_max3_f32 v4, v4, v69, v53
	v_max3_f32 v4, v4, v70, v54
	v_max3_f32 v4, v4, v71, v55
	v_max3_f32 v4, v4, v72, v56
	v_max3_f32 v4, v4, v73, v57
	v_max3_f32 v4, v4, v74, v58
	v_max3_f32 v4, v4, v75, v59
	v_max3_f32 v4, v4, v76, v60
	v_max3_f32 v4, v4, v77, v61
	v_max3_f32 v4, v4, v78, v62
	v_max3_f32 v4, v4, v79, v63
	ds_bpermute_b32 v5, v171, v4
	s_waitcnt lgkmcnt(0)
	v_max_f32_e32 v5, v5, v5
	v_max_f32_e32 v4, v4, v5
	v_cmp_lt_f32_e32 vcc, s26, v4
	s_cbranch_vccz .LBB0_580
	v_max_f32_e32 v4, v4, v4
	v_max_f32_e32 v4, 0, v4
	v_exp_f32_e64 v6, -v4
	v_pk_add_f32 v[64:65], v[64:65], v[4:5] op_sel_hi:[1,0] neg_lo:[0,1] neg_hi:[0,1]
	v_pk_add_f32 v[48:49], v[48:49], v[4:5] op_sel_hi:[1,0] neg_lo:[0,1] neg_hi:[0,1]
	v_pk_add_f32 v[66:67], v[66:67], v[4:5] op_sel_hi:[1,0] neg_lo:[0,1] neg_hi:[0,1]
	v_pk_add_f32 v[50:51], v[50:51], v[4:5] op_sel_hi:[1,0] neg_lo:[0,1] neg_hi:[0,1]
	v_pk_add_f32 v[68:69], v[68:69], v[4:5] op_sel_hi:[1,0] neg_lo:[0,1] neg_hi:[0,1]
	v_pk_add_f32 v[52:53], v[52:53], v[4:5] op_sel_hi:[1,0] neg_lo:[0,1] neg_hi:[0,1]
	v_pk_add_f32 v[70:71], v[70:71], v[4:5] op_sel_hi:[1,0] neg_lo:[0,1] neg_hi:[0,1]
	v_pk_add_f32 v[54:55], v[54:55], v[4:5] op_sel_hi:[1,0] neg_lo:[0,1] neg_hi:[0,1]
	v_pk_add_f32 v[72:73], v[72:73], v[4:5] op_sel_hi:[1,0] neg_lo:[0,1] neg_hi:[0,1]
	v_pk_add_f32 v[56:57], v[56:57], v[4:5] op_sel_hi:[1,0] neg_lo:[0,1] neg_hi:[0,1]
	v_pk_add_f32 v[74:75], v[74:75], v[4:5] op_sel_hi:[1,0] neg_lo:[0,1] neg_hi:[0,1]
	v_pk_add_f32 v[58:59], v[58:59], v[4:5] op_sel_hi:[1,0] neg_lo:[0,1] neg_hi:[0,1]
	v_pk_add_f32 v[76:77], v[76:77], v[4:5] op_sel_hi:[1,0] neg_lo:[0,1] neg_hi:[0,1]
	v_pk_add_f32 v[60:61], v[60:61], v[4:5] op_sel_hi:[1,0] neg_lo:[0,1] neg_hi:[0,1]
	v_pk_mul_f32 v[46:47], v[46:47], v[6:7] op_sel_hi:[1,0]
	v_pk_mul_f32 v[44:45], v[44:45], v[6:7] op_sel_hi:[1,0]
	v_pk_mul_f32 v[42:43], v[42:43], v[6:7] op_sel_hi:[1,0]
	v_pk_mul_f32 v[40:41], v[40:41], v[6:7] op_sel_hi:[1,0]
	v_pk_mul_f32 v[38:39], v[38:39], v[6:7] op_sel_hi:[1,0]
	v_pk_mul_f32 v[36:37], v[36:37], v[6:7] op_sel_hi:[1,0]
	v_pk_mul_f32 v[34:35], v[34:35], v[6:7] op_sel_hi:[1,0]
	v_pk_mul_f32 v[32:33], v[32:33], v[6:7] op_sel_hi:[1,0]
	v_pk_mul_f32 v[30:31], v[30:31], v[6:7] op_sel_hi:[1,0]
	v_pk_mul_f32 v[28:29], v[28:29], v[6:7] op_sel_hi:[1,0]
	v_pk_mul_f32 v[26:27], v[26:27], v[6:7] op_sel_hi:[1,0]
	v_pk_mul_f32 v[24:25], v[24:25], v[6:7] op_sel_hi:[1,0]
	v_pk_mul_f32 v[22:23], v[22:23], v[6:7] op_sel_hi:[1,0]
	v_pk_mul_f32 v[20:21], v[20:21], v[6:7] op_sel_hi:[1,0]
	v_pk_mul_f32 v[18:19], v[18:19], v[6:7] op_sel_hi:[1,0]
	v_pk_mul_f32 v[16:17], v[16:17], v[6:7] op_sel_hi:[1,0]
	v_pk_add_f32 v[78:79], v[78:79], v[4:5] op_sel_hi:[1,0] neg_lo:[0,1] neg_hi:[0,1]
	v_pk_add_f32 v[62:63], v[62:63], v[4:5] op_sel_hi:[1,0] neg_lo:[0,1] neg_hi:[0,1]
	v_mul_f32_e32 v3, v3, v6
	v_add_f32_e32 v0, v0, v4
.LBB0_580:
	v_add_u32_e32 v2, 0x8800, v2
	ds_read_b128 v[234:237], v2 offset:1024
	v_exp_f32_e32 v4, v64
	v_exp_f32_e32 v5, v65
	v_exp_f32_e32 v6, v66
	v_exp_f32_e32 v7, v67
	v_exp_f32_e32 v8, v68
	v_exp_f32_e32 v9, v69
	v_exp_f32_e32 v10, v70
	v_exp_f32_e32 v11, v71
	v_exp_f32_e32 v12, v72
	v_exp_f32_e32 v13, v73
	v_exp_f32_e32 v14, v74
	v_exp_f32_e32 v15, v75
	v_cvt_pk_bf16_f32 v68, v4, v5
	v_cvt_pk_bf16_f32 v69, v6, v7
	v_cvt_pk_bf16_f32 v70, v8, v9
	v_cvt_pk_bf16_f32 v71, v10, v11
	s_nop 1
	v_exp_f32_e32 v64, v76
	v_add_u32_e32 v76, 0x8800, v203
	v_add_u32_e32 v76, v76, v134
	ds_read_b128 v[238:241], v76 offset:1024
	ds_read_b128 v[242:245], v2 offset:1056
	ds_read_b128 v[246:249], v76 offset:1056
	s_waitcnt lgkmcnt(3)
	v_mfma_f32_32x32x16_bf16 v[32:47], v[234:237], v[68:71], v[32:47]
	ds_read_b128 v[234:237], v2 offset:1088
	v_exp_f32_e32 v65, v77
	v_exp_f32_e32 v66, v78
	v_exp_f32_e32 v67, v79
	v_exp_f32_e32 v48, v48
	v_exp_f32_e32 v49, v49
	v_exp_f32_e32 v50, v50
	s_waitcnt lgkmcnt(3)
	v_mfma_f32_32x32x16_bf16 v[16:31], v[238:241], v[68:71], v[16:31]
	ds_read_b128 v[238:241], v76 offset:1088
	v_cvt_pk_bf16_f32 v68, v12, v13
	v_cvt_pk_bf16_f32 v69, v14, v15
	v_cvt_pk_bf16_f32 v70, v64, v65
	v_cvt_pk_bf16_f32 v71, v66, v67
	s_nop 1
	v_exp_f32_e32 v51, v51
	v_exp_f32_e32 v52, v52
	v_exp_f32_e32 v53, v53
	v_exp_f32_e32 v54, v54
	v_exp_f32_e32 v55, v55
	s_waitcnt lgkmcnt(3)
	v_mfma_f32_32x32x16_bf16 v[32:47], v[242:245], v[68:71], v[32:47]
	ds_read_b128 v[242:245], v2 offset:1120
	v_exp_f32_e32 v56, v56
	v_exp_f32_e32 v57, v57
	v_exp_f32_e32 v58, v58
	v_exp_f32_e32 v59, v59
	v_exp_f32_e32 v60, v60
	v_exp_f32_e32 v61, v61
	s_waitcnt lgkmcnt(3)
	v_mfma_f32_32x32x16_bf16 v[16:31], v[246:249], v[68:71], v[16:31]
	ds_read_b128 v[246:249], v76 offset:1120
	v_cvt_pk_bf16_f32 v68, v48, v49
	v_cvt_pk_bf16_f32 v69, v50, v51
	v_cvt_pk_bf16_f32 v70, v52, v53
	v_cvt_pk_bf16_f32 v71, v54, v55
	s_nop 1
	v_exp_f32_e32 v62, v62
	v_exp_f32_e32 v63, v63
	s_add_i32 s29, s28, 2
	v_cmp_lt_u32_e64 s[6:7], s29, v204
	v_cmp_ge_u32_e32 vcc, s29, v204
	s_waitcnt lgkmcnt(3)
	v_mfma_f32_32x32x16_bf16 v[32:47], v[234:237], v[68:71], v[32:47]
	s_waitcnt lgkmcnt(2)
	v_mfma_f32_32x32x16_bf16 v[16:31], v[238:241], v[68:71], v[16:31]
	v_cvt_pk_bf16_f32 v68, v56, v57
	v_cvt_pk_bf16_f32 v69, v58, v59
	v_cvt_pk_bf16_f32 v70, v60, v61
	v_cvt_pk_bf16_f32 v71, v62, v63
	s_nop 1
	s_waitcnt lgkmcnt(1)
	v_mfma_f32_32x32x16_bf16 v[32:47], v[242:245], v[68:71], v[32:47]
	s_waitcnt lgkmcnt(0)
	v_mfma_f32_32x32x16_bf16 v[16:31], v[246:249], v[68:71], v[16:31]
	s_and_saveexec_b64 s[16:17], s[6:7]
	s_cbranch_execz .LBB0_584
	s_waitcnt vmcnt(3)
	ds_write_b128 v149, v[112:115]
	s_and_saveexec_b64 s[6:7], s[4:5]
	ds_write_b128 v202, v[116:119]
	s_or_b64 exec, exec, s[6:7]
	s_waitcnt vmcnt(2)
	ds_write_b64 v253, v[124:125] offset:13312
	ds_write_b64 v253, v[126:127] offset:13328
